# v15 + attention unit epilogue: eight output-gate loads hoisted and issued together, no waits on the interleaved stores (was 4x load-wait-store ladder)
# speedup vs baseline: 1.0038x; 1.0038x over previous
; __device__ __forceinline__ float bflo(unsigned v) { return __uint_as_float(v << 16); }
; __device__ __forceinline__ float bfhi(unsigned v) { return __uint_as_float(v & 0xffff0000u); }
; __device__ __forceinline__ unsigned pk2(float lo, float hi) { return pg8::cvt_pk_bf16(lo, hi); }
; __device__ __forceinline__ float fsigmoid(float x) { return __builtin_amdgcn_rcpf(1.0f + __builtin_amdgcn_exp2f(-LOG2E * x)); }
; __device__ __forceinline__ void fx_attn_unit(const Args& A, Frame& F, int bh, int qb, float qkmax) {
;     ...
;     l += __shfl_xor(l, 32);
;     const float inv = 1.0f / l;
;     bf16* XN = (bf16*)(A.ws + WS_XN);
;     const size_t row = (size_t)b * SEQ + tq;
; #pragma unroll
;     for (int rg = 0; rg < 4; ++rg) {
;         const int c0 = 8 * rg + 4 * hh;
;         const u32x2 ga = *(const u32x2*)(Og + (size_t)tq * 4096 + c0), gb2 = *(const u32x2*)(Og + (size_t)tq * 4096 + 32 + c0);
;         u32x2 wa, wb;
;         wa.x = pk2(o0[4 * rg] * inv * fsigmoid(bflo(ga.x)), o0[4 * rg + 1] * inv * fsigmoid(bfhi(ga.x))); wa.y = pk2(o0[4 * rg + 2] * inv * fsigmoid(bflo(ga.y)), o0[4 * rg + 3] * inv * fsigmoid(bfhi(ga.y)));
;         wb.x = pk2(o1[4 * rg] * inv * fsigmoid(bflo(gb2.x)), o1[4 * rg + 1] * inv * fsigmoid(bfhi(gb2.x))); wb.y = pk2(o1[4 * rg + 2] * inv * fsigmoid(bflo(gb2.y)), o1[4 * rg + 3] * inv * fsigmoid(bfhi(gb2.y)));
;         *(u32x2*)(XN + row * 1024 + hd * 64 + c0) = wa; *(u32x2*)(XN + row * 1024 + hd * 64 + 32 + c0) = wb;
;     }
.LBB0_672:
	ds_bpermute_b32 v0, v111, v217
	s_mov_b32 s25, s87
	s_waitcnt lgkmcnt(0)
	v_add_f32_e32 v0, v217, v0
	v_div_scale_f32 v34, s[0:1], v0, v0, 1.0
	v_rcp_f32_e32 v35, v34
	s_mov_b64 s[0:1], 0x1800
	v_fma_f32 v36, -v34, v35, 1.0
	v_fmac_f32_e32 v35, v36, v35
	v_div_scale_f32 v36, vcc, 1.0, v0, 1.0
	v_mul_f32_e32 v37, v36, v35
	v_fma_f32 v38, -v34, v37, v36
	v_fmac_f32_e32 v37, v38, v35
	v_fma_f32 v34, -v34, v37, v36
	v_div_fmas_f32 v34, v34, v35, v37
	v_lshl_add_u64 v[36:37], v[120:121], 0, s[22:23]
	v_div_fixup_f32 v34, v34, v0, 1.0
	v_lshlrev_b64 v[36:37], 11, v[36:37]
	v_lshlrev_b32_e32 v0, 1, v114
	v_lshl_add_u64 v[36:37], s[90:91], 0, v[36:37]
	v_lshl_add_u64 v[40:41], v[118:119], 0, v[0:1]
	v_lshl_add_u64 v[38:39], v[36:37], 0, s[24:25]
	v_lshl_add_u64 v[36:37], v[40:41], 0, s[0:1]
	v_add_co_u32_e32 v40, vcc, s59, v40
	s_mov_b64 s[0:1], 0
	s_nop 0
	v_addc_co_u32_e32 v41, vcc, 0, v41, vcc
	global_load_dwordx2 v[40:41], v[40:41], off offset:2048
	s_nop 0
	global_load_dwordx2 v[42:43], v[36:37], off offset:64
	global_load_dwordx2 v[46:47], v[36:37], off offset:16
	global_load_dwordx2 v[48:49], v[36:37], off offset:80
	global_load_dwordx2 v[50:51], v[36:37], off offset:32
	global_load_dwordx2 v[52:53], v[36:37], off offset:96
	global_load_dwordx2 v[54:55], v[36:37], off offset:48
	global_load_dwordx2 v[56:57], v[36:37], off offset:112
	s_waitcnt vmcnt(0)
	v_lshlrev_b32_e32 v35, 16, v40
	v_mul_f32_e32 v35, 0xbfb8aa3b, v35
	v_exp_f32_e32 v35, v35
	s_nop 0
	v_add_f32_e32 v35, 1.0, v35
	v_rcp_f32_e32 v44, v35
	v_and_b32_e32 v35, 0xffff0000, v40
	v_mul_f32_e32 v35, 0xbfb8aa3b, v35
	v_exp_f32_e32 v35, v35
	s_nop 0
	v_add_f32_e32 v35, 1.0, v35
	v_rcp_f32_e32 v45, v35
	v_pk_mul_f32 v[18:19], v[18:19], v[34:35] op_sel_hi:[1,0]
	v_pk_mul_f32 v[20:21], v[20:21], v[34:35] op_sel_hi:[1,0]
	v_pk_mul_f32 v[2:3], v[2:3], v[34:35] op_sel_hi:[1,0]
	v_pk_mul_f32 v[18:19], v[18:19], v[44:45]
	v_pk_mul_f32 v[4:5], v[4:5], v[34:35] op_sel_hi:[1,0]
	v_cvt_pk_bf16_f32 v18, v18, v19
	v_lshlrev_b32_e32 v19, 16, v41
	v_mul_f32_e32 v19, 0xbfb8aa3b, v19
	v_exp_f32_e32 v19, v19
	v_pk_mul_f32 v[22:23], v[22:23], v[34:35] op_sel_hi:[1,0]
	v_pk_mul_f32 v[6:7], v[6:7], v[34:35] op_sel_hi:[1,0]
	v_pk_mul_f32 v[8:9], v[8:9], v[34:35] op_sel_hi:[1,0]
	v_add_f32_e32 v19, 1.0, v19
	v_rcp_f32_e32 v40, v19
	v_and_b32_e32 v19, 0xffff0000, v41
	v_mul_f32_e32 v19, 0xbfb8aa3b, v19
	v_exp_f32_e32 v19, v19
	v_pk_mul_f32 v[10:11], v[10:11], v[34:35] op_sel_hi:[1,0]
	v_add_f32_e32 v19, 1.0, v19
	v_rcp_f32_e32 v41, v19
	s_nop 0
	v_pk_mul_f32 v[20:21], v[20:21], v[40:41]
	s_nop 0
	v_cvt_pk_bf16_f32 v19, v20, v21
	v_lshlrev_b32_e32 v20, 16, v42
	v_and_b32_e32 v21, 0xffff0000, v42
	v_mul_f32_e32 v20, 0xbfb8aa3b, v20
	v_mul_f32_e32 v21, 0xbfb8aa3b, v21
	v_exp_f32_e32 v20, v20
	v_exp_f32_e32 v21, v21
	v_add_f32_e32 v20, 1.0, v20
	v_add_f32_e32 v21, 1.0, v21
	v_rcp_f32_e32 v20, v20
	v_rcp_f32_e32 v21, v21
	s_nop 0
	v_pk_mul_f32 v[2:3], v[2:3], v[20:21]
	s_nop 0
	v_cvt_pk_bf16_f32 v20, v2, v3
	v_lshlrev_b32_e32 v2, 16, v43
	v_and_b32_e32 v3, 0xffff0000, v43
	v_mul_f32_e32 v2, 0xbfb8aa3b, v2
	v_mul_f32_e32 v3, 0xbfb8aa3b, v3
	v_exp_f32_e32 v2, v2
	v_exp_f32_e32 v3, v3
	v_add_f32_e32 v2, 1.0, v2
	v_add_f32_e32 v3, 1.0, v3
	v_rcp_f32_e32 v2, v2
	v_rcp_f32_e32 v3, v3
	s_nop 0
	v_pk_mul_f32 v[2:3], v[4:5], v[2:3]
	s_nop 0
	v_cvt_pk_bf16_f32 v21, v2, v3
	v_lshl_add_u64 v[2:3], v[38:39], 0, v[0:1]
	global_store_dwordx2 v[2:3], v[18:19], off
	global_store_dwordx2 v[2:3], v[20:21], off offset:64
	v_mov_b32_e32 v4, v46
	v_mov_b32_e32 v5, v47
	s_nop 0
	v_mov_b32_e32 v18, v48
	v_mov_b32_e32 v19, v49
	v_lshlrev_b32_e32 v0, 16, v4
	v_mul_f32_e32 v0, 0xbfb8aa3b, v0
	v_exp_f32_e32 v0, v0
	s_nop 0
	v_add_f32_e32 v0, 1.0, v0
	v_rcp_f32_e32 v20, v0
	v_and_b32_e32 v0, 0xffff0000, v4
	v_mul_f32_e32 v0, 0xbfb8aa3b, v0
	v_exp_f32_e32 v0, v0
	s_nop 0
	v_add_f32_e32 v0, 1.0, v0
	v_rcp_f32_e32 v21, v0
	v_lshlrev_b32_e32 v0, 16, v5
	v_mul_f32_e32 v0, 0xbfb8aa3b, v0
	v_exp_f32_e32 v0, v0
	v_pk_mul_f32 v[20:21], v[22:23], v[20:21]
	v_pk_mul_f32 v[22:23], v[24:25], v[34:35] op_sel_hi:[1,0]
	v_cvt_pk_bf16_f32 v4, v20, v21
	v_add_f32_e32 v0, 1.0, v0
	v_rcp_f32_e32 v20, v0
	v_and_b32_e32 v0, 0xffff0000, v5
	v_mul_f32_e32 v0, 0xbfb8aa3b, v0
	v_exp_f32_e32 v0, v0
	s_nop 0
	v_add_f32_e32 v0, 1.0, v0
	v_rcp_f32_e32 v21, v0
	v_lshlrev_b32_e32 v0, 16, v18
	v_mul_f32_e32 v0, 0xbfb8aa3b, v0
	v_exp_f32_e32 v0, v0
	v_pk_mul_f32 v[20:21], v[22:23], v[20:21]
; __device__ __forceinline__ float bflo(unsigned v) { return __uint_as_float(v << 16); }
; __device__ __forceinline__ float bfhi(unsigned v) { return __uint_as_float(v & 0xffff0000u); }
; __device__ __forceinline__ unsigned pk2(float lo, float hi) { return pg8::cvt_pk_bf16(lo, hi); }
; __device__ __forceinline__ float fsigmoid(float x) { return __builtin_amdgcn_rcpf(1.0f + __builtin_amdgcn_exp2f(-LOG2E * x)); }
; __device__ __forceinline__ void fx_attn_unit(const Args& A, Frame& F, int bh, int qb, float qkmax) {
;     ...
;     for (int rg = 0; rg < 4; ++rg) {
;         const int c0 = 8 * rg + 4 * hh;
;         const u32x2 ga = *(const u32x2*)(Og + (size_t)tq * 4096 + c0), gb2 = *(const u32x2*)(Og + (size_t)tq * 4096 + 32 + c0);
;         u32x2 wa, wb;
;         wa.x = pk2(o0[4 * rg] * inv * fsigmoid(bflo(ga.x)), o0[4 * rg + 1] * inv * fsigmoid(bfhi(ga.x))); wa.y = pk2(o0[4 * rg + 2] * inv * fsigmoid(bflo(ga.y)), o0[4 * rg + 3] * inv * fsigmoid(bfhi(ga.y)));
;         wb.x = pk2(o1[4 * rg] * inv * fsigmoid(bflo(gb2.x)), o1[4 * rg + 1] * inv * fsigmoid(bfhi(gb2.x))); wb.y = pk2(o1[4 * rg + 2] * inv * fsigmoid(bflo(gb2.y)), o1[4 * rg + 3] * inv * fsigmoid(bfhi(gb2.y)));
;         *(u32x2*)(XN + row * 1024 + hd * 64 + c0) = wa; *(u32x2*)(XN + row * 1024 + hd * 64 + 32 + c0) = wb;
;     }
	v_add_f32_e32 v0, 1.0, v0
	v_cvt_pk_bf16_f32 v5, v20, v21
	v_rcp_f32_e32 v20, v0
	v_and_b32_e32 v0, 0xffff0000, v18
	v_mul_f32_e32 v0, 0xbfb8aa3b, v0
	v_exp_f32_e32 v0, v0
	s_nop 0
	v_add_f32_e32 v0, 1.0, v0
	v_rcp_f32_e32 v21, v0
	v_lshlrev_b32_e32 v0, 16, v19
	v_mul_f32_e32 v0, 0xbfb8aa3b, v0
	v_exp_f32_e32 v0, v0
	v_pk_mul_f32 v[6:7], v[6:7], v[20:21]
	v_add_f32_e32 v0, 1.0, v0
	v_rcp_f32_e32 v18, v0
	v_and_b32_e32 v0, 0xffff0000, v19
	v_mul_f32_e32 v0, 0xbfb8aa3b, v0
	v_exp_f32_e32 v0, v0
	v_cvt_pk_bf16_f32 v6, v6, v7
	v_add_f32_e32 v0, 1.0, v0
	v_rcp_f32_e32 v19, v0
	s_nop 0
	v_pk_mul_f32 v[8:9], v[8:9], v[18:19]
	s_nop 0
	v_cvt_pk_bf16_f32 v7, v8, v9
	global_store_dwordx2 v[2:3], v[4:5], off offset:16
	global_store_dwordx2 v[2:3], v[6:7], off offset:80
	v_mov_b32_e32 v4, v50
	v_mov_b32_e32 v5, v51
	s_nop 0
	v_mov_b32_e32 v6, v52
	v_mov_b32_e32 v7, v53
	v_pk_mul_f32 v[18:19], v[26:27], v[34:35] op_sel_hi:[1,0]
	v_lshlrev_b32_e32 v0, 16, v4
	v_mul_f32_e32 v0, 0xbfb8aa3b, v0
	v_exp_f32_e32 v0, v0
	s_nop 0
	v_add_f32_e32 v0, 1.0, v0
	v_rcp_f32_e32 v8, v0
	v_and_b32_e32 v0, 0xffff0000, v4
	v_mul_f32_e32 v0, 0xbfb8aa3b, v0
	v_exp_f32_e32 v0, v0
	s_nop 0
	v_add_f32_e32 v0, 1.0, v0
	v_rcp_f32_e32 v9, v0
	v_lshlrev_b32_e32 v0, 16, v5
	v_mul_f32_e32 v0, 0xbfb8aa3b, v0
	v_exp_f32_e32 v0, v0
	v_pk_mul_f32 v[8:9], v[18:19], v[8:9]
	v_pk_mul_f32 v[18:19], v[28:29], v[34:35] op_sel_hi:[1,0]
	v_cvt_pk_bf16_f32 v4, v8, v9
	v_add_f32_e32 v0, 1.0, v0
	v_rcp_f32_e32 v8, v0
	v_and_b32_e32 v0, 0xffff0000, v5
	v_mul_f32_e32 v0, 0xbfb8aa3b, v0
	v_exp_f32_e32 v0, v0
	s_nop 0
	v_add_f32_e32 v0, 1.0, v0
	v_rcp_f32_e32 v9, v0
	v_lshlrev_b32_e32 v0, 16, v6
	v_mul_f32_e32 v0, 0xbfb8aa3b, v0
	v_exp_f32_e32 v0, v0
	v_pk_mul_f32 v[8:9], v[18:19], v[8:9]
	v_add_f32_e32 v0, 1.0, v0
	v_cvt_pk_bf16_f32 v5, v8, v9
	v_rcp_f32_e32 v8, v0
	v_and_b32_e32 v0, 0xffff0000, v6
	v_mul_f32_e32 v0, 0xbfb8aa3b, v0
	v_exp_f32_e32 v0, v0
	s_nop 0
	v_add_f32_e32 v0, 1.0, v0
	v_rcp_f32_e32 v9, v0
	v_lshlrev_b32_e32 v0, 16, v7
	v_mul_f32_e32 v0, 0xbfb8aa3b, v0
	v_exp_f32_e32 v0, v0
	v_pk_mul_f32 v[8:9], v[10:11], v[8:9]
	v_pk_mul_f32 v[10:11], v[12:13], v[34:35] op_sel_hi:[1,0]
	v_cvt_pk_bf16_f32 v6, v8, v9
	v_add_f32_e32 v0, 1.0, v0
	v_rcp_f32_e32 v8, v0
	v_and_b32_e32 v0, 0xffff0000, v7
	v_mul_f32_e32 v0, 0xbfb8aa3b, v0
	v_exp_f32_e32 v0, v0
	s_nop 0
	v_add_f32_e32 v0, 1.0, v0
	v_rcp_f32_e32 v9, v0
	s_nop 0
	v_pk_mul_f32 v[8:9], v[10:11], v[8:9]
	s_nop 0
	v_cvt_pk_bf16_f32 v7, v8, v9
	global_store_dwordx2 v[2:3], v[4:5], off offset:32
	global_store_dwordx2 v[2:3], v[6:7], off offset:96
	v_mov_b32_e32 v6, v54
	v_mov_b32_e32 v7, v55
	s_nop 0
	v_mov_b32_e32 v4, v56
	v_mov_b32_e32 v5, v57
	v_pk_mul_f32 v[10:11], v[30:31], v[34:35] op_sel_hi:[1,0]
	v_lshlrev_b32_e32 v0, 16, v6
	v_mul_f32_e32 v0, 0xbfb8aa3b, v0
	v_exp_f32_e32 v0, v0
	s_nop 0
	v_add_f32_e32 v0, 1.0, v0
	v_rcp_f32_e32 v8, v0
	v_and_b32_e32 v0, 0xffff0000, v6
	v_mul_f32_e32 v0, 0xbfb8aa3b, v0
	v_exp_f32_e32 v0, v0
	s_nop 0
	v_add_f32_e32 v0, 1.0, v0
	v_rcp_f32_e32 v9, v0
	v_lshlrev_b32_e32 v0, 16, v7
	v_mul_f32_e32 v0, 0xbfb8aa3b, v0
	v_exp_f32_e32 v0, v0
	v_pk_mul_f32 v[8:9], v[10:11], v[8:9]
	v_pk_mul_f32 v[10:11], v[32:33], v[34:35] op_sel_hi:[1,0]
	v_cvt_pk_bf16_f32 v6, v8, v9
	v_add_f32_e32 v0, 1.0, v0
	v_rcp_f32_e32 v8, v0
	v_and_b32_e32 v0, 0xffff0000, v7
	v_mul_f32_e32 v0, 0xbfb8aa3b, v0
	v_exp_f32_e32 v0, v0
	s_nop 0
	v_add_f32_e32 v0, 1.0, v0
	v_rcp_f32_e32 v9, v0
	v_lshlrev_b32_e32 v0, 16, v4
	v_mul_f32_e32 v0, 0xbfb8aa3b, v0
	v_exp_f32_e32 v0, v0
	v_pk_mul_f32 v[8:9], v[10:11], v[8:9]
	v_pk_mul_f32 v[10:11], v[14:15], v[34:35] op_sel_hi:[1,0]
	v_cvt_pk_bf16_f32 v7, v8, v9
	v_add_f32_e32 v0, 1.0, v0
	v_rcp_f32_e32 v8, v0
	v_and_b32_e32 v0, 0xffff0000, v4
	v_mul_f32_e32 v0, 0xbfb8aa3b, v0
	v_exp_f32_e32 v0, v0
	s_nop 0
	v_add_f32_e32 v0, 1.0, v0
	v_rcp_f32_e32 v9, v0
	v_lshlrev_b32_e32 v0, 16, v5
	v_mul_f32_e32 v0, 0xbfb8aa3b, v0
	v_exp_f32_e32 v0, v0
	v_pk_mul_f32 v[8:9], v[10:11], v[8:9]
	v_pk_mul_f32 v[10:11], v[16:17], v[34:35] op_sel_hi:[1,0]
	v_cvt_pk_bf16_f32 v4, v8, v9
	v_add_f32_e32 v0, 1.0, v0
	v_rcp_f32_e32 v8, v0
	v_and_b32_e32 v0, 0xffff0000, v5
	v_mul_f32_e32 v0, 0xbfb8aa3b, v0
	v_exp_f32_e32 v0, v0
	s_nop 0
	v_add_f32_e32 v0, 1.0, v0
	v_rcp_f32_e32 v9, v0
	s_nop 0
	v_pk_mul_f32 v[8:9], v[10:11], v[8:9]
	s_nop 0
	v_cvt_pk_bf16_f32 v5, v8, v9
	global_store_dwordx2 v[2:3], v[6:7], off offset:48
	global_store_dwordx2 v[2:3], v[4:5], off offset:112
